# phase 7 fused into phase 6: pre-norm tile kept in LDS, per-row-block group counter + PSUM exchange inside the XCD, out written once; barrier 6 and phase 7 removed (on top of write-through stores in P0
# speedup vs baseline: 1.1119x; 1.0117x over previous
; __device__ __forceinline__ unsigned cvtpk(float lo, float hi) { f32x2_t v = {lo, hi}; bf16x2_t b = __builtin_convertvector(v, bf16x2_t); return __builtin_bit_cast(unsigned, b); }
; __device__ __forceinline__ void phase0(const Params& p, unsigned char* smem) {
;     ...
;       int row = it * 4 + wave; int b = row / LTOK, pos = row - b * LTOK;
;       const float* src = pos < NMETA ? p.meta + pos * DM : p.x + ((size_t)b * SEQ + pos - NMETA) * DM;
;       float4 v[4]; float ss = 0.f;
; #pragma unroll
;       for (int i = 0; i < 4; ++i) { v[i] = ((const float4*)src)[lane + 64 * i]; ss += v[i].x * v[i].x + v[i].y * v[i].y + v[i].z * v[i].z + v[i].w * v[i].w; }
;       ss = wave_sum(ss);
;       float rs = rsqrtf(ss * (1.f / 1024.f) + 1e-6f);
; #pragma unroll
;       for (int i = 0; i < 4; ++i) {
;         float4 w = ((const float4*)p.norm_w)[lane + 64 * i];
;         uint2 o; o.x = cvtpk(v[i].x * rs * w.x, v[i].y * rs * w.y); o.y = cvtpk(v[i].z * rs * w.z, v[i].w * rs * w.w);
;         ((uint2*)(hn + (size_t)row * DM))[lane + 64 * i] = o;
;       }
.LBB0_2:
	s_or_b64 exec, exec, s[10:11]
	v_mov_b32_e32 v23, v7
	v_lshl_add_u64 v[30:31], v[28:29], 0, v[22:23]
	global_load_dwordx4 v[26:29], v[30:31], off
	global_load_dwordx4 v[52:55], v[30:31], off offset:1024
	global_load_dwordx4 v[56:59], v[30:31], off offset:2048
	global_load_dwordx4 v[60:63], v[30:31], off offset:3072
	v_and_b32_e32 v23, 64, v48
	v_xor_b32_e32 v25, 32, v48
	v_add_u32_e32 v23, 64, v23
	v_cmp_lt_i32_e32 vcc, v25, v23
	s_waitcnt vmcnt(3)
	v_mov_b32_e32 v72, v27
	s_waitcnt vmcnt(2)
	v_mov_b32_e32 v73, v53
	v_mov_b32_e32 v70, v26
	v_mov_b32_e32 v71, v52
	s_waitcnt vmcnt(1)
	v_mov_b32_e32 v80, v57
	s_waitcnt vmcnt(0)
	v_mov_b32_e32 v81, v61
	v_pk_mul_f32 v[72:73], v[72:73], v[72:73]
	v_mov_b32_e32 v30, v28
	v_mov_b32_e32 v31, v54
	v_mov_b32_e32 v78, v56
	v_mov_b32_e32 v79, v60
	v_pk_mul_f32 v[80:81], v[80:81], v[80:81]
	v_pk_fma_f32 v[70:71], v[70:71], v[70:71], v[72:73]
	v_mov_b32_e32 v68, v29
	v_mov_b32_e32 v69, v55
	v_mov_b32_e32 v74, v58
	v_mov_b32_e32 v75, v62
	v_pk_fma_f32 v[72:73], v[78:79], v[78:79], v[80:81]
	v_pk_fma_f32 v[30:31], v[30:31], v[30:31], v[70:71]
	v_mov_b32_e32 v76, v59
	v_mov_b32_e32 v77, v63
	v_pk_fma_f32 v[70:71], v[74:75], v[74:75], v[72:73]
	v_pk_fma_f32 v[30:31], v[68:69], v[68:69], v[30:31]
	v_pk_fma_f32 v[68:69], v[76:77], v[76:77], v[70:71]
	v_add_f32_e32 v30, v30, v31
	v_cndmask_b32_e32 v25, v48, v25, vcc
	v_add_f32_e32 v30, v30, v68
	v_lshlrev_b32_e32 v25, 2, v25
	v_add_f32_e32 v30, v30, v69
	ds_bpermute_b32 v25, v25, v30
	v_xor_b32_e32 v31, 16, v48
	v_cmp_lt_i32_e32 vcc, v31, v23
	s_waitcnt lgkmcnt(0)
	v_add_f32_e32 v25, v30, v25
	v_cndmask_b32_e32 v31, v48, v31, vcc
	v_lshlrev_b32_e32 v31, 2, v31
	ds_bpermute_b32 v30, v31, v25
	v_xor_b32_e32 v31, 8, v48
	v_cmp_lt_i32_e32 vcc, v31, v23
	s_waitcnt lgkmcnt(0)
	v_add_f32_e32 v25, v25, v30
	v_cndmask_b32_e32 v31, v48, v31, vcc
	v_lshlrev_b32_e32 v31, 2, v31
	ds_bpermute_b32 v30, v31, v25
	v_xor_b32_e32 v31, 4, v48
	v_cmp_lt_i32_e32 vcc, v31, v23
	s_waitcnt lgkmcnt(0)
	v_add_f32_e32 v25, v25, v30
	v_cndmask_b32_e32 v31, v48, v31, vcc
	v_lshlrev_b32_e32 v31, 2, v31
	ds_bpermute_b32 v30, v31, v25
	v_xor_b32_e32 v31, 2, v48
	v_cmp_lt_i32_e32 vcc, v31, v23
	s_waitcnt lgkmcnt(0)
	v_add_f32_e32 v25, v25, v30
	v_cndmask_b32_e32 v31, v48, v31, vcc
	v_lshlrev_b32_e32 v31, 2, v31
	ds_bpermute_b32 v30, v31, v25
	v_xor_b32_e32 v31, 1, v48
	v_cmp_lt_i32_e32 vcc, v31, v23
	s_waitcnt lgkmcnt(0)
	v_add_f32_e32 v25, v25, v30
	v_cndmask_b32_e32 v23, v48, v31, vcc
	v_lshlrev_b32_e32 v23, 2, v23
	ds_bpermute_b32 v23, v23, v25
	s_waitcnt lgkmcnt(0)
	v_add_f32_e32 v23, v25, v23
	v_fmamk_f32 v23, v23, 0x3a800000, v47
	v_mul_f32_e32 v25, 0x4b800000, v23
	v_cmp_gt_f32_e32 vcc, s58, v23
	s_nop 1
	v_cndmask_b32_e32 v23, v23, v25, vcc
	v_rsq_f32_e32 v23, v23
	v_ashrrev_i32_e32 v25, 31, v24
	v_lshlrev_b64 v[24:25], 11, v[24:25]
	v_lshl_add_u64 v[30:31], v[20:21], 0, v[24:25]
	v_mul_f32_e32 v24, 0x45800000, v23
	v_cndmask_b32_e32 v68, v23, v24, vcc
	v_pk_mul_f32 v[24:25], v[26:27], v[68:69] op_sel_hi:[1,0]
	v_pk_mul_f32 v[26:27], v[28:29], v[68:69] op_sel_hi:[1,0]
	v_pk_mul_f32 v[24:25], v[100:101], v[24:25]
	v_pk_mul_f32 v[26:27], v[102:103], v[26:27]
	v_cvt_pk_bf16_f32 v24, v24, v25
	v_cvt_pk_bf16_f32 v25, v26, v27
	global_store_dwordx2 v[30:31], v[24:25], off sc1
	v_pk_mul_f32 v[28:29], v[52:53], v[68:69] op_sel_hi:[1,0]
	v_pk_mul_f32 v[52:53], v[54:55], v[68:69] op_sel_hi:[1,0]
	v_pk_mul_f32 v[24:25], v[104:105], v[28:29]
	v_pk_mul_f32 v[26:27], v[106:107], v[52:53]
	v_cvt_pk_bf16_f32 v24, v24, v25
	v_cvt_pk_bf16_f32 v25, v26, v27
	global_store_dwordx2 v[30:31], v[24:25], off offset:512 sc1
	v_pk_mul_f32 v[28:29], v[56:57], v[68:69] op_sel_hi:[1,0]
	v_pk_mul_f32 v[52:53], v[58:59], v[68:69] op_sel_hi:[1,0]
	v_pk_mul_f32 v[24:25], v[28:29], v[108:109]
	v_pk_mul_f32 v[26:27], v[52:53], v[110:111]
	v_cvt_pk_bf16_f32 v24, v24, v25
	v_cvt_pk_bf16_f32 v25, v26, v27
	global_store_dwordx2 v[30:31], v[24:25], off offset:1024 sc1
	v_pk_mul_f32 v[28:29], v[60:61], v[68:69] op_sel_hi:[1,0]
	v_pk_mul_f32 v[52:53], v[62:63], v[68:69] op_sel_hi:[1,0]
	v_pk_mul_f32 v[24:25], v[28:29], v[112:113]
	v_pk_mul_f32 v[26:27], v[52:53], v[114:115]
	v_cvt_pk_bf16_f32 v24, v24, v25
	v_cvt_pk_bf16_f32 v25, v26, v27
	global_store_dwordx2 v[30:31], v[24:25], off offset:1536 sc1

; __device__ __forceinline__ void phase0(const Params& p, unsigned char* smem) {
;     ...
;       for (int idx = mi * 256 + tid; idx < 2 * 48 * 512; idx += N_MISC * 256) {
;         int b = idx / (48 * 512), r = idx - b * 48 * 512;
;         ak[((size_t)b * LPAD + LTOK) * 512 + r] = 0u;
;       }
.LBB0_9:
	v_mul_hi_i32 v30, v26, s46
	v_mul_hi_i32 v31, v27, s46
	v_lshrrev_b32_e32 v51, 31, v30
	v_ashrrev_i32_e32 v30, 12, v30
	v_lshrrev_b32_e32 v52, 31, v31
	v_ashrrev_i32_e32 v31, 12, v31
	v_add_u32_e32 v51, v30, v51
	v_add_u32_e32 v31, v31, v52
	v_mul_i32_i24_e32 v56, 0x2040, v51
	v_mul_i32_i24_e32 v54, 0x2040, v31
	v_ashrrev_i32_e32 v57, 31, v56
	v_add_u32_e32 v29, -2, v29
	v_mad_i32_i24 v30, v51, s47, v26
	v_ashrrev_i32_e32 v55, 31, v54
	v_lshlrev_b64 v[56:57], 11, v[56:57]
	v_cmp_eq_u32_e64 s[10:11], 0, v29
	v_mad_i32_i24 v52, v31, s47, v27
	v_ashrrev_i32_e32 v31, 31, v30
	v_lshlrev_b64 v[54:55], 11, v[54:55]
	v_lshl_add_u64 v[56:57], s[24:25], 0, v[56:57]
	s_or_b64 s[38:39], s[10:11], s[38:39]
	v_add_u32_e32 v27, 0x2000, v27
	v_add_u32_e32 v26, 0x2000, v26
	v_ashrrev_i32_e32 v53, 31, v52
	v_lshl_add_u64 v[54:55], s[24:25], 0, v[54:55]
	v_lshl_add_u64 v[30:31], v[30:31], 2, v[56:57]
	v_lshl_add_u64 v[52:53], v[52:53], 2, v[54:55]
	global_store_dword v[30:31], v7, off sc1
	global_store_dword v[52:53], v7, off sc1
	s_andn2_b64 exec, exec, s[38:39]
	s_cbranch_execnz .LBB0_9
	s_or_b64 exec, exec, s[38:39]
	v_and_b32_e32 v27, 0x1ffffe, v28
	v_cmp_ne_u32_e64 s[10:11], v28, v27
	v_lshl_add_u32 v26, v27, 12, v24
	s_orn2_b64 s[10:11], s[10:11], exec

; __device__ __forceinline__ void phase0(const Params& p, unsigned char* smem) {
;     ...
;       for (int idx = mi * 256 + tid; idx < 2 * 48 * 512; idx += N_MISC * 256) {
;         int b = idx / (48 * 512), r = idx - b * 48 * 512;
;         ak[((size_t)b * LPAD + LTOK) * 512 + r] = 0u;
;       }
.LBB0_13:
	v_mul_hi_i32 v27, v26, s46
	v_lshrrev_b32_e32 v30, 31, v27
	v_ashrrev_i32_e32 v27, 12, v27
	v_add_u32_e32 v27, v27, v30
	v_mul_i32_i24_e32 v52, 0x2040, v27
	v_ashrrev_i32_e32 v53, 31, v52
	v_mad_i32_i24 v30, v27, s47, v26
	v_lshlrev_b64 v[52:53], 11, v[52:53]
	v_add_u32_e32 v29, 0x1000, v26
	v_cmp_lt_i32_e64 s[10:11], s52, v26
	v_ashrrev_i32_e32 v31, 31, v30
	v_lshl_add_u64 v[52:53], s[24:25], 0, v[52:53]
	s_or_b64 s[38:39], s[10:11], s[38:39]
	v_mov_b32_e32 v26, v29
	v_lshl_add_u64 v[30:31], v[30:31], 2, v[52:53]
	global_store_dword v[30:31], v7, off sc1
	s_andn2_b64 exec, exec, s[38:39]
	s_cbranch_execnz .LBB0_13

; __device__ __forceinline__ void phase0(const Params& p, unsigned char* smem) {
;     ...
;       for (int idx = mi * 256 + tid; idx < 2048 * 24; idx += N_MISC * 256) {
;         int row = idx / 24, c = idx - row * 24;
;         avt[(size_t)row * (LPAD / 2) + LTOK / 2 + c] = 0u;
;       }
.LBB0_16:
	v_mul_hi_i32 v25, v26, s46
	v_mul_hi_i32 v29, v27, s46
	v_lshrrev_b32_e32 v31, 31, v25
	v_ashrrev_i32_e32 v25, 2, v25
	v_lshrrev_b32_e32 v51, 31, v29
	v_ashrrev_i32_e32 v29, 2, v29
	v_add_u32_e32 v25, v25, v31
	v_mov_b32_e32 v30, v27
	v_mov_b64_e32 v[52:53], s[26:27]
	v_add_u32_e32 v23, -2, v23
	v_add_u32_e32 v29, v29, v51
	v_mad_u64_u32 v[54:55], s[38:39], v25, s53, v[26:27]
	v_cmp_eq_u32_e32 vcc, 0, v23
	v_mad_u64_u32 v[30:31], s[38:39], v29, s53, v[30:31]
	v_mad_i64_i32 v[56:57], s[38:39], v25, s54, v[52:53]
	v_ashrrev_i32_e32 v55, 31, v54
	s_or_b64 s[36:37], vcc, s[36:37]
	v_mad_i64_i32 v[52:53], s[38:39], v29, s54, v[52:53]
	v_add_u32_e32 v27, 0x2000, v27
	v_add_u32_e32 v26, 0x2000, v26
	v_ashrrev_i32_e32 v31, 31, v30
	v_lshl_add_u64 v[54:55], v[54:55], 2, v[56:57]
	v_lshl_add_u64 v[30:31], v[30:31], 2, v[52:53]
	global_store_dword v[54:55], v7, off sc1
	global_store_dword v[30:31], v7, off sc1
	s_andn2_b64 exec, exec, s[36:37]
	s_cbranch_execnz .LBB0_16
	s_or_b64 exec, exec, s[36:37]
	v_and_b32_e32 v23, 0x1ffffe, v28
	v_cmp_ne_u32_e32 vcc, v28, v23
	v_lshl_add_u32 v24, v23, 12, v24
	s_orn2_b64 s[36:37], vcc, exec

; __device__ __forceinline__ void phase0(const Params& p, unsigned char* smem) {
;     ...
;       for (int idx = mi * 256 + tid; idx < 2048 * 24; idx += N_MISC * 256) {
;         int row = idx / 24, c = idx - row * 24;
;         avt[(size_t)row * (LPAD / 2) + LTOK / 2 + c] = 0u;
;       }
;       if (mi == 0) {
;         int* ctl = (int*)(p.ws + OFF_CTL);
;         if (tid < 16) ctl[tid] = 0;
;         if (wave == 1) {
;           float a = p.lq1[lane] * p.lk1[lane], c = p.lq2[lane] * p.lk2[lane];
;           a = wave_sum(a); c = wave_sum(c);
;           if (lane == 0) ((float*)ctl)[16] = __expf(a) - __expf(c) + 0.2f;
.LBB0_20:
	v_mul_hi_i32 v23, v24, s46
	v_lshrrev_b32_e32 v28, 31, v23
	v_ashrrev_i32_e32 v23, 2, v23
	v_add_u32_e32 v25, 0x1000, v24
	v_add_u32_e32 v23, v23, v28
	v_mov_b64_e32 v[26:27], s[26:27]
	v_mad_u64_u32 v[28:29], s[36:37], v23, s53, v[24:25]
	v_cmp_lt_i32_e32 vcc, s52, v24
	v_mad_i64_i32 v[26:27], s[36:37], v23, s54, v[26:27]
	v_ashrrev_i32_e32 v29, 31, v28
	s_or_b64 s[10:11], vcc, s[10:11]
	v_mov_b32_e32 v24, v25
	v_lshl_add_u64 v[26:27], v[28:29], 2, v[26:27]
	global_store_dword v[26:27], v7, off sc1
	s_andn2_b64 exec, exec, s[10:11]
	s_cbranch_execnz .LBB0_20
.LBB0_21:
	s_or_b64 exec, exec, s[34:35]
	s_cmp_eq_u32 s20, 0
	s_cbranch_scc0 .LBB0_28
	s_and_saveexec_b64 s[10:11], s[8:9]
	s_cbranch_execz .LBB0_24
	global_store_dword v[8:9], v7, off sc1
.LBB0_24:
	s_or_b64 exec, exec, s[10:11]
	s_and_saveexec_b64 s[10:11], s[4:5]
	s_cbranch_execz .LBB0_27
	global_load_dword v23, v[10:11], off
	global_load_dword v24, v[12:13], off
	s_waitcnt lgkmcnt(0)
	global_load_dword v25, v[14:15], off
	global_load_dword v26, v[16:17], off
	v_and_b32_e32 v27, 64, v48
	v_xor_b32_e32 v28, 32, v48
	v_add_u32_e32 v27, 64, v27
	v_cmp_lt_i32_e32 vcc, v28, v27
	v_xor_b32_e32 v29, 16, v48
	v_xor_b32_e32 v30, 8, v48
	v_cndmask_b32_e32 v28, v48, v28, vcc
	v_lshlrev_b32_e32 v28, 2, v28
	v_cmp_lt_i32_e32 vcc, v29, v27
	v_xor_b32_e32 v31, 4, v48
	v_xor_b32_e32 v51, 2, v48
	v_cndmask_b32_e32 v29, v48, v29, vcc
	v_lshlrev_b32_e32 v29, 2, v29
	v_cmp_lt_i32_e32 vcc, v30, v27
	v_xor_b32_e32 v52, 1, v48
	s_waitcnt vmcnt(2)
	v_mul_f32_e32 v53, v23, v24
	ds_bpermute_b32 v53, v28, v53
	s_waitcnt vmcnt(0)
	v_mul_f32_e32 v54, v25, v26
	ds_bpermute_b32 v28, v28, v54
	s_waitcnt lgkmcnt(1)
	v_fmac_f32_e32 v53, v23, v24
	ds_bpermute_b32 v23, v29, v53
	s_waitcnt lgkmcnt(1)
	v_fmac_f32_e32 v28, v25, v26
	ds_bpermute_b32 v24, v29, v28
	v_cndmask_b32_e32 v25, v48, v30, vcc
	v_lshlrev_b32_e32 v25, 2, v25
	s_waitcnt lgkmcnt(1)
	v_add_f32_e32 v23, v53, v23
	ds_bpermute_b32 v26, v25, v23
	s_waitcnt lgkmcnt(1)
	v_add_f32_e32 v24, v28, v24
	ds_bpermute_b32 v25, v25, v24
	v_cmp_lt_i32_e32 vcc, v31, v27
	s_waitcnt lgkmcnt(1)
	v_add_f32_e32 v23, v23, v26
	v_cndmask_b32_e32 v28, v48, v31, vcc
	v_lshlrev_b32_e32 v28, 2, v28
	s_waitcnt lgkmcnt(0)
	v_add_f32_e32 v24, v24, v25
	ds_bpermute_b32 v25, v28, v23
	ds_bpermute_b32 v26, v28, v24
	v_cmp_lt_i32_e32 vcc, v51, v27
	s_waitcnt lgkmcnt(1)
	v_add_f32_e32 v23, v23, v25
	v_cndmask_b32_e32 v28, v48, v51, vcc
	v_lshlrev_b32_e32 v28, 2, v28
	s_waitcnt lgkmcnt(0)
	v_add_f32_e32 v25, v24, v26
	ds_bpermute_b32 v24, v28, v23
	ds_bpermute_b32 v26, v28, v25
	v_cmp_lt_i32_e32 vcc, v52, v27
	s_waitcnt lgkmcnt(1)
	v_add_f32_e32 v24, v23, v24
	v_cndmask_b32_e32 v27, v48, v52, vcc
	v_lshlrev_b32_e32 v27, 2, v27
	s_waitcnt lgkmcnt(0)
	v_add_f32_e32 v23, v25, v26
	ds_bpermute_b32 v26, v27, v24
	ds_bpermute_b32 v25, v27, v23
	s_and_b64 exec, exec, s[6:7]
	s_cbranch_execz .LBB0_27
	s_waitcnt lgkmcnt(1)
	v_add_f32_e32 v24, v24, v26
	s_waitcnt lgkmcnt(0)
	v_add_f32_e32 v23, v23, v25
	v_mul_f32_e32 v24, 0x3fb8aa3b, v24
	v_mul_f32_e32 v23, 0x3fb8aa3b, v23
	v_exp_f32_e32 v24, v24
	v_exp_f32_e32 v23, v23
	s_nop 0
	v_sub_f32_e32 v23, v24, v23
	v_add_f32_e32 v23, 0x3e4ccccd, v23
	global_store_dword v7, v23, s[28:29] sc1

; __device__ __forceinline__ unsigned cvtpk(float lo, float hi) { f32x2_t v = {lo, hi}; bf16x2_t b = __builtin_convertvector(v, bf16x2_t); return __builtin_bit_cast(unsigned, b); }
; __device__ __forceinline__ void phase0(const Params& p, unsigned char* smem) {
;     ...
;       float* tile = (float*)smem;
; #pragma unroll
;       for (int i = 0; i < 16; ++i) {
;         int k = (tid >> 6) + 4 * i; int n = nt * 64 + (tid & 63);
;         tile[k * 65 + (tid & 63)] = n < N ? W[(size_t)(kt * 64 + k) * N + n] : 0.f;
;       }
;       __syncthreads();
;       int kk2 = (tid & 31) * 2;
; #pragma unroll
;       for (int i = 0; i < 8; ++i) {
;         int jj = (tid >> 5) + 8 * i; int n = nt * 64 + jj;
;         if (n < N) *(unsigned*)(Wt + (size_t)n * 1024 + kt * 64 + kk2) = cvtpk(tile[kk2 * 65 + jj], tile[(kk2 + 1) * 65 + jj]);
;       }
.LBB0_50:
	s_or_b64 exec, exec, s[34:35]
	s_lshl_b32 s34, s39, 1
	s_add_u32 s10, s10, s34
	s_waitcnt vmcnt(1)
	ds_write_b32 v49, v23 offset:14560
	s_waitcnt vmcnt(0)
	ds_write_b32 v49, v26 offset:15600
	s_addc_u32 s11, s11, 0
	v_add_u32_e32 v26, s38, v5
	v_lshl_add_u64 v[24:25], s[10:11], 0, v[6:7]
	v_cmp_gt_i32_e32 vcc, s20, v26
	s_waitcnt lgkmcnt(0)
	s_barrier
	s_and_saveexec_b64 s[10:11], vcc
	s_cbranch_execz .LBB0_52
	ds_read2_b32 v[28:29], v44 offset1:65
	v_ashrrev_i32_e32 v27, 31, v26
	v_lshlrev_b64 v[30:31], 11, v[26:27]
	s_waitcnt lgkmcnt(0)
	v_cvt_pk_bf16_f32 v23, v28, v29
	v_lshl_add_u64 v[28:29], v[24:25], 0, v[30:31]
	global_store_dword v[28:29], v23, off sc1
.LBB0_52:
	s_or_b64 exec, exec, s[10:11]
	v_add_u32_e32 v28, 8, v26
	v_cmp_gt_i32_e32 vcc, s20, v28
	s_and_saveexec_b64 s[10:11], vcc
	s_cbranch_execz .LBB0_54
	ds_read2_b32 v[30:31], v44 offset0:8 offset1:73
	v_ashrrev_i32_e32 v29, 31, v28
	v_lshlrev_b64 v[28:29], 11, v[28:29]
	v_lshl_add_u64 v[28:29], v[24:25], 0, v[28:29]
	s_waitcnt lgkmcnt(0)
	v_cvt_pk_bf16_f32 v23, v30, v31
	global_store_dword v[28:29], v23, off sc1
.LBB0_54:
	s_or_b64 exec, exec, s[10:11]
	v_add_u32_e32 v28, 16, v26
	v_cmp_gt_i32_e32 vcc, s20, v28
	s_and_saveexec_b64 s[10:11], vcc
	s_cbranch_execz .LBB0_56
	ds_read2_b32 v[30:31], v44 offset0:16 offset1:81
	v_ashrrev_i32_e32 v29, 31, v28
	v_lshlrev_b64 v[28:29], 11, v[28:29]
	v_lshl_add_u64 v[28:29], v[24:25], 0, v[28:29]
	s_waitcnt lgkmcnt(0)
	v_cvt_pk_bf16_f32 v23, v30, v31
	global_store_dword v[28:29], v23, off sc1
.LBB0_56:
	s_or_b64 exec, exec, s[10:11]
	v_add_u32_e32 v28, 24, v26
	v_cmp_gt_i32_e32 vcc, s20, v28
	s_and_saveexec_b64 s[10:11], vcc
	s_cbranch_execz .LBB0_58
	ds_read2_b32 v[30:31], v44 offset0:24 offset1:89
	v_ashrrev_i32_e32 v29, 31, v28
	v_lshlrev_b64 v[28:29], 11, v[28:29]
	v_lshl_add_u64 v[28:29], v[24:25], 0, v[28:29]
	s_waitcnt lgkmcnt(0)
	v_cvt_pk_bf16_f32 v23, v30, v31
	global_store_dword v[28:29], v23, off sc1
.LBB0_58:
	s_or_b64 exec, exec, s[10:11]
	v_add_u32_e32 v28, 32, v26
	v_cmp_gt_i32_e32 vcc, s20, v28
	s_and_saveexec_b64 s[10:11], vcc
	s_cbranch_execz .LBB0_60
	ds_read2_b32 v[30:31], v44 offset0:32 offset1:97
	v_ashrrev_i32_e32 v29, 31, v28
	v_lshlrev_b64 v[28:29], 11, v[28:29]
	v_lshl_add_u64 v[28:29], v[24:25], 0, v[28:29]
	s_waitcnt lgkmcnt(0)
	v_cvt_pk_bf16_f32 v23, v30, v31
	global_store_dword v[28:29], v23, off sc1
.LBB0_60:
	s_or_b64 exec, exec, s[10:11]
	v_add_u32_e32 v28, 40, v26
	v_cmp_gt_i32_e32 vcc, s20, v28
	s_and_saveexec_b64 s[10:11], vcc
	s_cbranch_execz .LBB0_62
	ds_read2_b32 v[30:31], v44 offset0:40 offset1:105
	v_ashrrev_i32_e32 v29, 31, v28
	v_lshlrev_b64 v[28:29], 11, v[28:29]
	v_lshl_add_u64 v[28:29], v[24:25], 0, v[28:29]
	s_waitcnt lgkmcnt(0)
	v_cvt_pk_bf16_f32 v23, v30, v31
	global_store_dword v[28:29], v23, off sc1
.LBB0_62:
	s_or_b64 exec, exec, s[10:11]
	v_add_u32_e32 v28, 48, v26
	v_cmp_gt_i32_e32 vcc, s20, v28
	s_and_saveexec_b64 s[10:11], vcc
	s_cbranch_execz .LBB0_64
	ds_read2_b32 v[30:31], v44 offset0:48 offset1:113
	v_ashrrev_i32_e32 v29, 31, v28
	v_lshlrev_b64 v[28:29], 11, v[28:29]
	v_lshl_add_u64 v[28:29], v[24:25], 0, v[28:29]
	s_waitcnt lgkmcnt(0)
	v_cvt_pk_bf16_f32 v23, v30, v31
	global_store_dword v[28:29], v23, off sc1
.LBB0_64:
	s_or_b64 exec, exec, s[10:11]
	v_add_u32_e32 v26, 56, v26
	v_cmp_gt_i32_e32 vcc, s20, v26
	s_and_saveexec_b64 s[10:11], vcc
	s_cbranch_execz .LBB0_66
	ds_read2_b32 v[28:29], v44 offset0:56 offset1:121
	v_ashrrev_i32_e32 v27, 31, v26
	v_lshlrev_b64 v[26:27], 11, v[26:27]
	v_lshl_add_u64 v[24:25], v[24:25], 0, v[26:27]
	s_waitcnt lgkmcnt(0)
	v_cvt_pk_bf16_f32 v23, v28, v29
	global_store_dword v[24:25], v23, off sc1

; __device__ __forceinline__ void grid_barrier(unsigned* ctr, const unsigned k) {
;   __syncthreads();
;   if (threadIdx.x == 0) {
;     __hip_atomic_fetch_add(ctr, 1u, __ATOMIC_RELEASE, __HIP_MEMORY_SCOPE_AGENT);
;     const unsigned target = k * gridDim.x;
;     while (__hip_atomic_load(ctr, __ATOMIC_RELAXED, __HIP_MEMORY_SCOPE_AGENT) < target) __builtin_amdgcn_s_sleep(1);
;     __builtin_amdgcn_fence(__ATOMIC_ACQUIRE, "agent");
;   }
;   __syncthreads();
.LBB0_73:
	s_waitcnt vmcnt(0) lgkmcnt(0)
	s_barrier
	v_cmp_eq_u32_e32 vcc, 0, v218
	s_and_saveexec_b64 s[4:5], vcc
	s_cbranch_execz .LBB0_83
	s_add_u32 s6, s50, 0xf223cb0
	s_addc_u32 s7, s51, 0
	s_waitcnt vmcnt(0)
	v_mov_b32_e32 v0, 0
	v_mov_b32_e32 v1, 1
	global_atomic_add v1, v0, v1, s[6:7] sc0
	s_waitcnt vmcnt(0)
	v_readfirstlane_b32 s8, v1
	s_nop 3
	s_add_i32 s8, s8, 1
	s_cmp_eq_u32 s8, s3
	s_cbranch_scc0 .Lgbar1_poll
	v_mov_b32_e32 v1, 1
	global_atomic_add v0, v1, s[6:7] offset:80
	global_atomic_add v0, v1, s[6:7] offset:144
	global_atomic_add v0, v1, s[6:7] offset:208
	global_atomic_add v0, v1, s[6:7] offset:272
	global_atomic_add v0, v1, s[6:7] offset:336
	global_atomic_add v0, v1, s[6:7] offset:400
	global_atomic_add v0, v1, s[6:7] offset:464
	global_atomic_add v0, v1, s[6:7] offset:528
	s_branch .Lgbar1_done

; __device__ __forceinline__ void phase6(const Params& p, unsigned char* smem) {
;   const u16* MERGED = (const u16*)(p.ws + OFF_EXTRA);
;   const u16* wot = (const u16*)(p.ws + OFF_W3) + 2 * 1024 * 1024;
;   float* PSUM = (float*)(p.ws + OFF_PSUM);
;   const int xcd = blockIdx.x & 7, lw = blockIdx.x >> 3, LW = (gridDim.x - xcd + 7) >> 3;
;   for (int i = lw;; i += LW) {
;     int mt, nt; if (!tile_map(i, xcd, 128, 8, mt, nt)) break;
;     const int m0 = mt * 128, n0 = nt * 128;
;     f32x16 acc[2][2]; zero_acc(acc);
;     gemm_kloop(acc, [&](int m) { return MERGED + (size_t)m * 1024; }, [](int k0) { return (size_t)k0; }, wot, m0, n0, smem);
.LBB0_424:
	s_or_b64 exec, exec, s[6:7]
	s_andn2_b64 vcc, exec, s[4:5]
	s_barrier
	s_cbranch_vccnz .LBB0_441
	s_add_u32 s4, s36, 0xc5d9000
	s_addc_u32 s5, s37, 0
	s_add_u32 s6, s36, 0xec1d000
	s_addc_u32 s7, s37, 0
	s_add_u32 s2, s36, 0xf123000
	s_addc_u32 s26, s37, 0
	s_lshr_b32 s8, s89, 6
	s_and_b32 s22, s8, 8
	s_load_dwordx2 s[8:9], s[0:1], 0x0
	s_load_dwordx2 s[10:11], s[0:1], 0x88
	s_load_dwordx2 s[54:55], s[0:1], 0x80
	s_mov_b64 s[56:57], 0x10000
	s_mov_b32 s61, 0
	s_lshl_b32 s27, s73, 7
	s_add_u32 s12, s36, 0xc5d9080
	s_addc_u32 s13, s37, 0
	v_mov_b32_e32 v97, 0
	s_mov_b64 s[14:15], 0x10000
	s_mov_b64 s[16:17], 0x20000
	s_mov_b64 s[18:19], 0x30000
	s_mov_b32 s28, 0x10000
	s_mov_b32 s29, 0x20000
	s_mov_b32 s30, 0x30000
	s_movk_i32 s31, 0x90
	s_mov_b32 s34, 0xfffffc0
	s_movk_i32 s35, 0x210
	s_branch .LBB0_428

; __device__ __forceinline__ int ltid() { int t = threadIdx.x; asm volatile("" : "+v"(t)); return t; }
; __device__ __forceinline__ void phase6(const Params& p, unsigned char* smem) {
;     ...
;     epilogue_rows(acc, m0, n0, smem, [&](int m, int n, float4 a, float4 b) {
;       const float4* xp = (const float4*)(p.x + (size_t)m * 1024 + n);
;       float4 x0 = xp[0], x1 = xp[1];
;       a.x += x0.x; a.y += x0.y; a.z += x0.z; a.w += x0.w; b.x += x1.x; b.y += x1.y; b.z += x1.z; b.w += x1.w;
;       float4* op = (float4*)(p.out + (size_t)m * 1024 + n);
;       op[0] = a; op[1] = b;
;       float sq = a.x * a.x + a.y * a.y + a.z * a.z + a.w * a.w + b.x * b.x + b.y * b.y + b.z * b.z + b.w * b.w;
;       sq += __shfl_xor(sq, 1); sq += __shfl_xor(sq, 2); sq += __shfl_xor(sq, 4); sq += __shfl_xor(sq, 8);
;       if ((ltid() & 15) == 0) PSUM[(size_t)nt * NX + m] = sq;
;     });
.LBB0_437:
	v_add_u32_e32 v12, s24, v1
	s_waitcnt lgkmcnt(0)
	v_ashrrev_i32_e32 v13, 4, v12
	v_add_u32_e32 v6, s38, v13
	v_ashrrev_i32_e32 v7, 31, v6
	v_lshlrev_b64 v[30:31], 12, v[6:7]
	v_lshl_add_u64 v[22:23], v[2:3], 0, v[30:31]
	global_load_dwordx4 v[14:17], v[22:23], off
	global_load_dwordx4 v[18:21], v[22:23], off offset:16
	v_mad_u64_u32 v[26:27], s[22:23], v13, s35, v[0:1]
	v_mov_b32_e32 v140, v26
	ds_read_b128 v[22:25], v26
	ds_read_b128 v[26:29], v26 offset:16
	s_waitcnt vmcnt(1) lgkmcnt(1)
	v_pk_add_f32 v[14:15], v[22:23], v[14:15]
	v_pk_add_f32 v[16:17], v[24:25], v[16:17]
	v_pk_mul_f32 v[22:23], v[14:15], v[14:15]
	v_pk_mul_f32 v[24:25], v[16:17], v[16:17]
	v_add_f32_e32 v13, v22, v23
	s_waitcnt vmcnt(0) lgkmcnt(0)
	v_pk_add_f32 v[18:19], v[26:27], v[18:19]
	v_add_f32_e32 v13, v13, v24
	v_pk_mul_f32 v[26:27], v[18:19], v[18:19]
	v_add_f32_e32 v13, v13, v25
	v_pk_add_f32 v[20:21], v[28:29], v[20:21]
	v_add_f32_e32 v13, v13, v26
	v_pk_mul_f32 v[28:29], v[20:21], v[20:21]
	v_add_f32_e32 v13, v13, v27
	v_add_f32_e32 v13, v13, v28
	v_add_f32_e32 v13, v13, v29
	ds_bpermute_b32 v22, v8, v13
	s_waitcnt lgkmcnt(0)
	v_add_f32_e32 v13, v13, v22
	ds_bpermute_b32 v22, v9, v13
	s_waitcnt lgkmcnt(0)
	v_add_f32_e32 v13, v13, v22
	ds_bpermute_b32 v24, v10, v13
	v_lshl_add_u64 v[22:23], v[4:5], 0, v[30:31]
	ds_write_b128 v140, v[14:17]
	ds_write_b128 v140, v[18:21] offset:16
	s_waitcnt lgkmcnt(0)
	v_add_f32_e32 v13, v13, v24
	ds_bpermute_b32 v14, v11, v13
	v_mov_b32_e32 v15, v218
	s_nop 0
	v_and_b32_e32 v15, 15, v15
	v_cmp_eq_u32_e32 vcc, 0, v15
	s_and_saveexec_b64 s[22:23], vcc
	s_cbranch_execz .LBB0_439
	s_waitcnt lgkmcnt(0)
	v_add_f32_e32 v13, v13, v14
	v_lshl_add_u64 v[6:7], v[6:7], 2, s[20:21]
	global_store_dword v[6:7], v13, off sc1
.LBB0_439:
	s_or_b64 exec, exec, s[22:23]
	v_add_u32_e32 v6, 0x100, v12
	v_ashrrev_i32_e32 v22, 4, v6
	v_add_u32_e32 v6, s38, v22
	v_ashrrev_i32_e32 v7, 31, v6
	v_lshlrev_b64 v[28:29], 12, v[6:7]
	v_lshl_add_u64 v[20:21], v[2:3], 0, v[28:29]
	s_waitcnt lgkmcnt(0)
	global_load_dwordx4 v[12:15], v[20:21], off
	global_load_dwordx4 v[16:19], v[20:21], off offset:16
	v_mad_u64_u32 v[24:25], s[22:23], v22, s35, v[0:1]
	v_mov_b32_e32 v141, v24
	ds_read_b128 v[20:23], v24
	ds_read_b128 v[24:27], v24 offset:16
	s_waitcnt vmcnt(1) lgkmcnt(1)
	v_pk_add_f32 v[12:13], v[20:21], v[12:13]
	v_pk_add_f32 v[14:15], v[22:23], v[14:15]
	v_pk_mul_f32 v[20:21], v[12:13], v[12:13]
	v_pk_mul_f32 v[22:23], v[14:15], v[14:15]
	v_add_f32_e32 v20, v20, v21
	s_waitcnt vmcnt(0) lgkmcnt(0)
	v_pk_add_f32 v[16:17], v[24:25], v[16:17]
	v_add_f32_e32 v20, v20, v22
	v_pk_mul_f32 v[24:25], v[16:17], v[16:17]
	v_add_f32_e32 v20, v20, v23
	v_pk_add_f32 v[18:19], v[26:27], v[18:19]
	v_add_f32_e32 v20, v20, v24
	v_pk_mul_f32 v[26:27], v[18:19], v[18:19]
	v_add_f32_e32 v20, v20, v25
	v_add_f32_e32 v20, v20, v26
	v_add_f32_e32 v20, v20, v27
	ds_bpermute_b32 v21, v8, v20
	s_waitcnt lgkmcnt(0)
	v_add_f32_e32 v20, v20, v21
	ds_bpermute_b32 v21, v9, v20
	s_waitcnt lgkmcnt(0)
	v_add_f32_e32 v22, v20, v21
	ds_bpermute_b32 v23, v10, v22
	v_lshl_add_u64 v[20:21], v[4:5], 0, v[28:29]
	ds_write_b128 v141, v[12:15]
	ds_write_b128 v141, v[16:19] offset:16
	s_nop 0
	v_mov_b32_e32 v14, v218
	s_waitcnt lgkmcnt(0)
	v_add_f32_e32 v12, v22, v23
	ds_bpermute_b32 v13, v11, v12
	s_nop 0
	v_and_b32_e32 v14, 15, v14
	v_cmp_eq_u32_e32 vcc, 0, v14
	s_and_saveexec_b64 s[22:23], vcc
	s_cbranch_execz .LBB0_436
	s_waitcnt lgkmcnt(0)
	v_add_f32_e32 v12, v12, v13
	v_lshl_add_u64 v[6:7], v[6:7], 2, s[20:21]
	global_store_dword v[6:7], v12, off sc1
	s_branch .LBB0_436
.Lp6_norm:
	s_waitcnt vmcnt(0) lgkmcnt(0)
	s_barrier
	v_cmp_eq_u32_e32 vcc, 0, v218
	s_and_saveexec_b64 s[40:41], vcc
	s_cbranch_execz .Lp6_go
	s_and_b32 s60, s89, 7
	s_lshl_b32 s60, s60, 3
	s_bfe_u32 s62, s89, 0x30003
	s_or_b32 s60, s60, s62
	s_lshl_b32 s60, s60, 2
	v_mov_b32_e32 v182, s60
	v_mov_b32_e32 v183, 1
	global_atomic_add v182, v183, s[44:45] offset:1792
	s_add_i32 s61, s61, 8
	s_mov_b32 s62, 0
.Lp6_poll:
	global_load_dword v184, v182, s[44:45] offset:1792 sc1
	s_waitcnt vmcnt(0)
	v_cmp_le_u32_e32 vcc, s61, v184
	s_cbranch_vccnz .Lp6_go
	s_sleep 1
	s_add_u32 s62, s62, 1
	s_cmp_lt_u32 s62, 0x40000
	s_cbranch_scc1 .Lp6_poll
.Lp6_go:
	s_or_b64 exec, exec, s[40:41]
	s_barrier
; __device__ __forceinline__ int ltid() { int t = threadIdx.x; asm volatile("" : "+v"(t)); return t; }
; __device__ __forceinline__ void phase7(const Params& p) {
;   const float* PSUM = (const float*)(p.ws + OFF_PSUM);
;   const int tid__ = ltid(); const int lane = tid__ & 63, wave = tid__ >> 6;
;   for (int it = blockIdx.x; it < NX / 4; it += gridDim.x) {
;     int row = it * 4 + wave;
;     float tot = 0.f;
; #pragma unroll
;     for (int j = 0; j < 8; ++j) tot += PSUM[(size_t)j * NX + row];
;     float rs = rsqrtf(tot * (1.f / 1024.f) + 1e-6f);
;     float4* o = (float4*)(p.out + (size_t)row * 1024);
; #pragma unroll
;     for (int i = 0; i < 4; ++i) {
;       float4 v = o[lane + 64 * i]; float4 w = ((const float4*)p.final_w)[lane + 64 * i];
;       v.x *= rs * w.x; v.y *= rs * w.y; v.z *= rs * w.z; v.w *= rs * w.w;
;       o[lane + 64 * i] = v;
;     }
	v_lshrrev_b32_e32 v182, 4, v218
	v_and_b32_e32 v183, 15, v218
	v_mul_u32_u24_e32 v150, 0x210, v182
	v_lshl_add_u32 v150, v183, 5, v150
	v_add_u32_e32 v150, 16, v150
	v_add_u32_e32 v182, s38, v182
	v_and_b32_e32 v151, 7, v218
	v_lshlrev_b32_e32 v151, 16, v151
	v_lshl_add_u32 v151, v182, 2, v151
	v_mov_b32_e32 v152, v182
	v_ashrrev_i32_e32 v153, 31, v182
	v_lshlrev_b64 v[152:153], 12, v[152:153]
	v_lshl_add_u64 v[152:153], v[4:5], 0, v[152:153]
	s_sub_u32 s63, s20, s2
	s_lshr_b32 s63, s63, 16
	s_lshl_b32 s63, s63, 9
	v_lshl_add_u32 v162, v183, 5, s63
	s_mov_b32 s58, s2
	s_mov_b32 s59, s26
	global_load_dwordx4 v[154:157], v162, s[54:55]
	global_load_dwordx4 v[158:161], v162, s[54:55] offset:16
	v_mov_b32_e32 v165, 0
	global_load_dword v163, v151, s[58:59] offset:0 sc1
	ds_read_b128 v[166:169], v150 offset:0
	ds_read_b128 v[170:173], v150 offset:16
	s_waitcnt vmcnt(0)
	s_nop 1
	v_add_f32_dpp v163, v163, v163 row_ror:4 row_mask:0xf bank_mask:0xf
	s_nop 1
	v_add_f32_dpp v163, v163, v163 row_ror:2 row_mask:0xf bank_mask:0xf
	s_nop 1
	v_add_f32_dpp v163, v163, v163 row_ror:1 row_mask:0xf bank_mask:0xf
	v_mov_b32_e32 v182, 0x358637bd
	v_fmamk_f32 v163, v163, 0x3a800000, v182
	v_mul_f32_e32 v182, 0x4b800000, v163
	v_cmp_gt_f32_e32 vcc, 0x800000, v163
	s_nop 1
	v_cndmask_b32_e32 v163, v163, v182, vcc
	v_rsq_f32_e32 v163, v163
	s_nop 0
	v_mul_f32_e32 v182, 0x45800000, v163
	v_cndmask_b32_e32 v164, v163, v182, vcc
	v_pk_mul_f32 v[174:175], v[154:155], v[164:165] op_sel_hi:[1,0]
	v_pk_mul_f32 v[176:177], v[156:157], v[164:165] op_sel_hi:[1,0]
	v_pk_mul_f32 v[178:179], v[158:159], v[164:165] op_sel_hi:[1,0]
	v_pk_mul_f32 v[180:181], v[160:161], v[164:165] op_sel_hi:[1,0]
	s_waitcnt lgkmcnt(0)
	v_pk_mul_f32 v[174:175], v[166:167], v[174:175]
	v_pk_mul_f32 v[176:177], v[168:169], v[176:177]
	v_pk_mul_f32 v[178:179], v[170:171], v[178:179]
	v_pk_mul_f32 v[180:181], v[172:173], v[180:181]
	global_store_dwordx4 v[152:153], v[174:177], off
	global_store_dwordx4 v[152:153], v[178:181], off offset:16
	v_lshl_add_u64 v[152:153], v[152:153], 0, s[56:57]
	global_load_dword v163, v151, s[58:59] offset:64 sc1
	ds_read_b128 v[166:169], v150 offset:8448
	ds_read_b128 v[170:173], v150 offset:8464
	s_waitcnt vmcnt(0)
	s_nop 1
	v_add_f32_dpp v163, v163, v163 row_ror:4 row_mask:0xf bank_mask:0xf
	s_nop 1
	v_add_f32_dpp v163, v163, v163 row_ror:2 row_mask:0xf bank_mask:0xf
	s_nop 1
	v_add_f32_dpp v163, v163, v163 row_ror:1 row_mask:0xf bank_mask:0xf
	v_mov_b32_e32 v182, 0x358637bd
	v_fmamk_f32 v163, v163, 0x3a800000, v182
	v_mul_f32_e32 v182, 0x4b800000, v163
	v_cmp_gt_f32_e32 vcc, 0x800000, v163
	s_nop 1
	v_cndmask_b32_e32 v163, v163, v182, vcc
	v_rsq_f32_e32 v163, v163
	s_nop 0
	v_mul_f32_e32 v182, 0x45800000, v163
	v_cndmask_b32_e32 v164, v163, v182, vcc
	v_pk_mul_f32 v[174:175], v[154:155], v[164:165] op_sel_hi:[1,0]
	v_pk_mul_f32 v[176:177], v[156:157], v[164:165] op_sel_hi:[1,0]
	v_pk_mul_f32 v[178:179], v[158:159], v[164:165] op_sel_hi:[1,0]
	v_pk_mul_f32 v[180:181], v[160:161], v[164:165] op_sel_hi:[1,0]
	s_waitcnt lgkmcnt(0)
	v_pk_mul_f32 v[174:175], v[166:167], v[174:175]
	v_pk_mul_f32 v[176:177], v[168:169], v[176:177]
	v_pk_mul_f32 v[178:179], v[170:171], v[178:179]
	v_pk_mul_f32 v[180:181], v[172:173], v[180:181]
	global_store_dwordx4 v[152:153], v[174:177], off
	global_store_dwordx4 v[152:153], v[178:181], off offset:16
	v_lshl_add_u64 v[152:153], v[152:153], 0, s[56:57]
	global_load_dword v163, v151, s[58:59] offset:128 sc1
	ds_read_b128 v[166:169], v150 offset:16896
	ds_read_b128 v[170:173], v150 offset:16912
	s_waitcnt vmcnt(0)
	s_nop 1
	v_add_f32_dpp v163, v163, v163 row_ror:4 row_mask:0xf bank_mask:0xf
	s_nop 1
	v_add_f32_dpp v163, v163, v163 row_ror:2 row_mask:0xf bank_mask:0xf
	s_nop 1
	v_add_f32_dpp v163, v163, v163 row_ror:1 row_mask:0xf bank_mask:0xf
	v_mov_b32_e32 v182, 0x358637bd
	v_fmamk_f32 v163, v163, 0x3a800000, v182
	v_mul_f32_e32 v182, 0x4b800000, v163
	v_cmp_gt_f32_e32 vcc, 0x800000, v163
	s_nop 1
	v_cndmask_b32_e32 v163, v163, v182, vcc
	v_rsq_f32_e32 v163, v163
	s_nop 0
	v_mul_f32_e32 v182, 0x45800000, v163
	v_cndmask_b32_e32 v164, v163, v182, vcc
	v_pk_mul_f32 v[174:175], v[154:155], v[164:165] op_sel_hi:[1,0]
	v_pk_mul_f32 v[176:177], v[156:157], v[164:165] op_sel_hi:[1,0]
	v_pk_mul_f32 v[178:179], v[158:159], v[164:165] op_sel_hi:[1,0]
	v_pk_mul_f32 v[180:181], v[160:161], v[164:165] op_sel_hi:[1,0]
	s_waitcnt lgkmcnt(0)
	v_pk_mul_f32 v[174:175], v[166:167], v[174:175]
	v_pk_mul_f32 v[176:177], v[168:169], v[176:177]
	v_pk_mul_f32 v[178:179], v[170:171], v[178:179]
	v_pk_mul_f32 v[180:181], v[172:173], v[180:181]
	global_store_dwordx4 v[152:153], v[174:177], off
	global_store_dwordx4 v[152:153], v[178:181], off offset:16
	v_lshl_add_u64 v[152:153], v[152:153], 0, s[56:57]
	global_load_dword v163, v151, s[58:59] offset:192 sc1
	ds_read_b128 v[166:169], v150 offset:25344
	ds_read_b128 v[170:173], v150 offset:25360
	s_waitcnt vmcnt(0)
	s_nop 1
	v_add_f32_dpp v163, v163, v163 row_ror:4 row_mask:0xf bank_mask:0xf
	s_nop 1
	v_add_f32_dpp v163, v163, v163 row_ror:2 row_mask:0xf bank_mask:0xf
	s_nop 1
	v_add_f32_dpp v163, v163, v163 row_ror:1 row_mask:0xf bank_mask:0xf
	v_mov_b32_e32 v182, 0x358637bd
	v_fmamk_f32 v163, v163, 0x3a800000, v182
	v_mul_f32_e32 v182, 0x4b800000, v163
	v_cmp_gt_f32_e32 vcc, 0x800000, v163
	s_nop 1
	v_cndmask_b32_e32 v163, v163, v182, vcc
	v_rsq_f32_e32 v163, v163
	s_nop 0
	v_mul_f32_e32 v182, 0x45800000, v163
	v_cndmask_b32_e32 v164, v163, v182, vcc
	v_pk_mul_f32 v[174:175], v[154:155], v[164:165] op_sel_hi:[1,0]
	v_pk_mul_f32 v[176:177], v[156:157], v[164:165] op_sel_hi:[1,0]
	v_pk_mul_f32 v[178:179], v[158:159], v[164:165] op_sel_hi:[1,0]
	v_pk_mul_f32 v[180:181], v[160:161], v[164:165] op_sel_hi:[1,0]
	s_waitcnt lgkmcnt(0)
; __device__ __forceinline__ void phase7(const Params& p) {
;     ...
;   for (int it = blockIdx.x; it < NX / 4; it += gridDim.x) {
;     int row = it * 4 + wave;
;     float tot = 0.f;
; #pragma unroll
;     for (int j = 0; j < 8; ++j) tot += PSUM[(size_t)j * NX + row];
;     float rs = rsqrtf(tot * (1.f / 1024.f) + 1e-6f);
;     float4* o = (float4*)(p.out + (size_t)row * 1024);
; #pragma unroll
;     for (int i = 0; i < 4; ++i) {
;       float4 v = o[lane + 64 * i]; float4 w = ((const float4*)p.final_w)[lane + 64 * i];
;       v.x *= rs * w.x; v.y *= rs * w.y; v.z *= rs * w.z; v.w *= rs * w.w;
;       o[lane + 64 * i] = v;
;     }
	v_pk_mul_f32 v[174:175], v[166:167], v[174:175]
	v_pk_mul_f32 v[176:177], v[168:169], v[176:177]
	v_pk_mul_f32 v[178:179], v[170:171], v[178:179]
	v_pk_mul_f32 v[180:181], v[172:173], v[180:181]
	global_store_dwordx4 v[152:153], v[174:177], off
	global_store_dwordx4 v[152:153], v[178:181], off offset:16
	v_lshl_add_u64 v[152:153], v[152:153], 0, s[56:57]
	global_load_dword v163, v151, s[58:59] offset:256 sc1
	ds_read_b128 v[166:169], v150 offset:33792
	ds_read_b128 v[170:173], v150 offset:33808
	s_waitcnt vmcnt(0)
	s_nop 1
	v_add_f32_dpp v163, v163, v163 row_ror:4 row_mask:0xf bank_mask:0xf
	s_nop 1
	v_add_f32_dpp v163, v163, v163 row_ror:2 row_mask:0xf bank_mask:0xf
	s_nop 1
	v_add_f32_dpp v163, v163, v163 row_ror:1 row_mask:0xf bank_mask:0xf
	v_mov_b32_e32 v182, 0x358637bd
	v_fmamk_f32 v163, v163, 0x3a800000, v182
	v_mul_f32_e32 v182, 0x4b800000, v163
	v_cmp_gt_f32_e32 vcc, 0x800000, v163
	s_nop 1
	v_cndmask_b32_e32 v163, v163, v182, vcc
	v_rsq_f32_e32 v163, v163
	s_nop 0
	v_mul_f32_e32 v182, 0x45800000, v163
	v_cndmask_b32_e32 v164, v163, v182, vcc
	v_pk_mul_f32 v[174:175], v[154:155], v[164:165] op_sel_hi:[1,0]
	v_pk_mul_f32 v[176:177], v[156:157], v[164:165] op_sel_hi:[1,0]
	v_pk_mul_f32 v[178:179], v[158:159], v[164:165] op_sel_hi:[1,0]
	v_pk_mul_f32 v[180:181], v[160:161], v[164:165] op_sel_hi:[1,0]
	s_waitcnt lgkmcnt(0)
	v_pk_mul_f32 v[174:175], v[166:167], v[174:175]
	v_pk_mul_f32 v[176:177], v[168:169], v[176:177]
	v_pk_mul_f32 v[178:179], v[170:171], v[178:179]
	v_pk_mul_f32 v[180:181], v[172:173], v[180:181]
	global_store_dwordx4 v[152:153], v[174:177], off
	global_store_dwordx4 v[152:153], v[178:181], off offset:16
	v_lshl_add_u64 v[152:153], v[152:153], 0, s[56:57]
	global_load_dword v163, v151, s[58:59] offset:320 sc1
	ds_read_b128 v[166:169], v150 offset:42240
	ds_read_b128 v[170:173], v150 offset:42256
	s_waitcnt vmcnt(0)
	s_nop 1
	v_add_f32_dpp v163, v163, v163 row_ror:4 row_mask:0xf bank_mask:0xf
	s_nop 1
	v_add_f32_dpp v163, v163, v163 row_ror:2 row_mask:0xf bank_mask:0xf
	s_nop 1
	v_add_f32_dpp v163, v163, v163 row_ror:1 row_mask:0xf bank_mask:0xf
	v_mov_b32_e32 v182, 0x358637bd
	v_fmamk_f32 v163, v163, 0x3a800000, v182
	v_mul_f32_e32 v182, 0x4b800000, v163
	v_cmp_gt_f32_e32 vcc, 0x800000, v163
	s_nop 1
	v_cndmask_b32_e32 v163, v163, v182, vcc
	v_rsq_f32_e32 v163, v163
	s_nop 0
	v_mul_f32_e32 v182, 0x45800000, v163
	v_cndmask_b32_e32 v164, v163, v182, vcc
	v_pk_mul_f32 v[174:175], v[154:155], v[164:165] op_sel_hi:[1,0]
	v_pk_mul_f32 v[176:177], v[156:157], v[164:165] op_sel_hi:[1,0]
	v_pk_mul_f32 v[178:179], v[158:159], v[164:165] op_sel_hi:[1,0]
	v_pk_mul_f32 v[180:181], v[160:161], v[164:165] op_sel_hi:[1,0]
	s_waitcnt lgkmcnt(0)
	v_pk_mul_f32 v[174:175], v[166:167], v[174:175]
	v_pk_mul_f32 v[176:177], v[168:169], v[176:177]
	v_pk_mul_f32 v[178:179], v[170:171], v[178:179]
	v_pk_mul_f32 v[180:181], v[172:173], v[180:181]
	global_store_dwordx4 v[152:153], v[174:177], off
	global_store_dwordx4 v[152:153], v[178:181], off offset:16
	v_lshl_add_u64 v[152:153], v[152:153], 0, s[56:57]
	global_load_dword v163, v151, s[58:59] offset:384 sc1
	ds_read_b128 v[166:169], v150 offset:50688
	ds_read_b128 v[170:173], v150 offset:50704
	s_waitcnt vmcnt(0)
	s_nop 1
	v_add_f32_dpp v163, v163, v163 row_ror:4 row_mask:0xf bank_mask:0xf
	s_nop 1
	v_add_f32_dpp v163, v163, v163 row_ror:2 row_mask:0xf bank_mask:0xf
	s_nop 1
	v_add_f32_dpp v163, v163, v163 row_ror:1 row_mask:0xf bank_mask:0xf
	v_mov_b32_e32 v182, 0x358637bd
	v_fmamk_f32 v163, v163, 0x3a800000, v182
	v_mul_f32_e32 v182, 0x4b800000, v163
	v_cmp_gt_f32_e32 vcc, 0x800000, v163
	s_nop 1
	v_cndmask_b32_e32 v163, v163, v182, vcc
	v_rsq_f32_e32 v163, v163
	s_nop 0
	v_mul_f32_e32 v182, 0x45800000, v163
	v_cndmask_b32_e32 v164, v163, v182, vcc
	v_pk_mul_f32 v[174:175], v[154:155], v[164:165] op_sel_hi:[1,0]
	v_pk_mul_f32 v[176:177], v[156:157], v[164:165] op_sel_hi:[1,0]
	v_pk_mul_f32 v[178:179], v[158:159], v[164:165] op_sel_hi:[1,0]
	v_pk_mul_f32 v[180:181], v[160:161], v[164:165] op_sel_hi:[1,0]
	s_waitcnt lgkmcnt(0)
	v_pk_mul_f32 v[174:175], v[166:167], v[174:175]
	v_pk_mul_f32 v[176:177], v[168:169], v[176:177]
	v_pk_mul_f32 v[178:179], v[170:171], v[178:179]
	v_pk_mul_f32 v[180:181], v[172:173], v[180:181]
	global_store_dwordx4 v[152:153], v[174:177], off
	global_store_dwordx4 v[152:153], v[178:181], off offset:16
	v_lshl_add_u64 v[152:153], v[152:153], 0, s[56:57]
	global_load_dword v163, v151, s[58:59] offset:448 sc1
	ds_read_b128 v[166:169], v150 offset:59136
	ds_read_b128 v[170:173], v150 offset:59152
	s_waitcnt vmcnt(0)
	s_nop 1
	v_add_f32_dpp v163, v163, v163 row_ror:4 row_mask:0xf bank_mask:0xf
	s_nop 1
	v_add_f32_dpp v163, v163, v163 row_ror:2 row_mask:0xf bank_mask:0xf
	s_nop 1
	v_add_f32_dpp v163, v163, v163 row_ror:1 row_mask:0xf bank_mask:0xf
	v_mov_b32_e32 v182, 0x358637bd
	v_fmamk_f32 v163, v163, 0x3a800000, v182
	v_mul_f32_e32 v182, 0x4b800000, v163
	v_cmp_gt_f32_e32 vcc, 0x800000, v163
	s_nop 1
	v_cndmask_b32_e32 v163, v163, v182, vcc
	v_rsq_f32_e32 v163, v163
	s_nop 0
	v_mul_f32_e32 v182, 0x45800000, v163
	v_cndmask_b32_e32 v164, v163, v182, vcc
	v_pk_mul_f32 v[174:175], v[154:155], v[164:165] op_sel_hi:[1,0]
	v_pk_mul_f32 v[176:177], v[156:157], v[164:165] op_sel_hi:[1,0]
	v_pk_mul_f32 v[178:179], v[158:159], v[164:165] op_sel_hi:[1,0]
	v_pk_mul_f32 v[180:181], v[160:161], v[164:165] op_sel_hi:[1,0]
	s_waitcnt lgkmcnt(0)
	v_pk_mul_f32 v[174:175], v[166:167], v[174:175]
	v_pk_mul_f32 v[176:177], v[168:169], v[176:177]
	v_pk_mul_f32 v[178:179], v[170:171], v[178:179]
	v_pk_mul_f32 v[180:181], v[172:173], v[180:181]
	global_store_dwordx4 v[152:153], v[174:177], off
	global_store_dwordx4 v[152:153], v[178:181], off offset:16
	s_branch .LBB0_426
.LBB0_441:
	s_endpgm
	s_waitcnt lgkmcnt(0)
	s_waitcnt vmcnt(0)
	s_barrier
	s_and_saveexec_b64 s[4:5], s[42:43]
	s_cbranch_execz .LBB0_447
	s_waitcnt vmcnt(0)
	v_mov_b32_e32 v0, 0
	v_mov_b32_e32 v1, 1
	global_atomic_add v1, v0, v1, s[44:45] sc0
	s_mul_i32 s2, s3, 5
	s_waitcnt vmcnt(0)
	v_readfirstlane_b32 s6, v1
	s_nop 3
	s_add_i32 s6, s6, 1
	s_cmp_eq_u32 s6, s2
	s_cbranch_scc0 .Lgbar6_poll
	v_mov_b32_e32 v1, 1
	global_atomic_add v0, v1, s[44:45] offset:1280
	global_atomic_add v0, v1, s[44:45] offset:1344
	global_atomic_add v0, v1, s[44:45] offset:1408
	global_atomic_add v0, v1, s[44:45] offset:1472
	global_atomic_add v0, v1, s[44:45] offset:1536
	global_atomic_add v0, v1, s[44:45] offset:1600
	global_atomic_add v0, v1, s[44:45] offset:1664
	global_atomic_add v0, v1, s[44:45] offset:1728
	s_branch .Lgbar6_done
